# v61 + LRU-final unit reuses the conv tile its own workgroup left in LDS in the summary phase (dead recompute removed)
# speedup vs baseline: 1.0056x; 1.0056x over previous
; __device__ __forceinline__ int opaque_tid() { int t = threadIdx.x; asm volatile("" : "+v"(t)); return t; }
; __device__ __forceinline__ void lru_conv_tile(const Args& a, LAS bf16_t* cxb, int l, const Tile& T) {
;     const int tid = opaque_tid(), vec = tid & 31, grp = tid >> 5, c0 = vec * 8;
;     const bf16_t* PX = (const bf16_t*)(a.ws + WS_PX);
;     const float* caw = a.in[9] + (size_t)l * 4 * 256; const float* cab = a.in[10] + (size_t)l * 256;
;     u32x4 raw[11];
; #pragma unroll
;     for (int i = 0; i < 11; ++i) { const int tg = T.t0 + grp * 8 + i - 2, tgc = min(max(tg, 0), T.seqlen - 1); raw[i] = *(const u32x4*)(PX + (size_t)(T.rowbase + tgc) * DIN + c0); }
;     float w[4][8], bias[8], win[4][8];
; #pragma unroll
;     for (int k = 0; k < 4; ++k) { const f32x4 w0 = *(const f32x4*)(caw + k * 256 + c0), w1 = *(const f32x4*)(caw + k * 256 + c0 + 4);
; #pragma unroll
;         for (int e = 0; e < 4; ++e) { w[k][e] = w0[e]; w[k][4 + e] = w1[e]; } }
;     { const f32x4 b0 = *(const f32x4*)(cab + c0), b1 = *(const f32x4*)(cab + c0 + 4);
; #pragma unroll
;       for (int e = 0; e < 4; ++e) { bias[e] = b0[e]; bias[4 + e] = b1[e]; } }
.LBB0_541:
	s_or_b64 exec, exec, s[0:1]
	s_waitcnt vmcnt(0)
	v_mov_b32_e32 v66, v0
	s_nop 0
	v_ashrrev_i32_e32 v159, 2, v66
	v_and_b32_e32 v160, -8, v159
	v_add_u32_e32 v158, s72, v160
	s_nop 0
	s_nop 0
	s_nop 3
	v_cmp_gt_i32_e64 s[0:1], 2, v158
	v_cmp_lt_i32_e32 vcc, 1, v158
	s_and_saveexec_b64 s[4:5], vcc
	s_cbranch_execz .LBB0_543
	s_nop 2
	v_cmp_lt_u32_e32 vcc, s34, v158
	s_andn2_b64 s[0:1], s[0:1], exec
	s_and_b64 s[36:37], vcc, exec
	s_or_b64 s[0:1], s[0:1], s[36:37]

; #define LAS __attribute__((address_space(3)))
; __device__ __forceinline__ u32x4 pack8(const float (&f)[8]) { u32x4 o; o.x = pk2(f[0], f[1]); o.y = pk2(f[2], f[3]); o.z = pk2(f[4], f[5]); o.w = pk2(f[6], f[7]); return o; }
; __device__ __forceinline__ void lru_conv_tile(const Args& a, LAS bf16_t* cxb, int l, const Tile& T) {
;     ...
;     for (int i = 0; i < 11; ++i) {
;         const int tg = T.t0 + grp * 8 + i - 2;
;         u32x4 rv = raw[i]; if (!(tg >= 0 && tg < T.seqlen)) rv = (u32x4){0u, 0u, 0u, 0u};
; #pragma unroll
;         for (int e = 0; e < 8; ++e) { win[0][e] = win[1][e]; win[1][e] = win[2][e]; win[2][e] = win[3][e]; }
;         unpack8(rv, win[3]);
;         if (i >= 3) {
;             float o[8];
; #pragma unroll
;             for (int e = 0; e < 8; ++e) o[e] = bias[e] + w[0][e] * win[0][e] + w[1][e] * win[1][e] + w[2][e] * win[2][e] + w[3][e] * win[3][e];
;             *(LAS u32x4*)(cxb + (grp * 8 + i - 3) * CXS + c0) = pack8(o);
;         }
;     }
; template <int MODE>
; __device__ __forceinline__ void lru_unit(const Args& a, LAS unsigned char* lds, int l, int tt) {
;     ...
;     for (int nt = 0; nt < 2; ++nt) { prm0[nt][2] = -8.0f * log1pf(__expf(-prm0[nt][2])); prm1[nt][2] = -8.0f * log1pf(__expf(-prm1[nt][2])); }
;     __syncthreads();
.LBB0_545:
	s_nop 1
	s_or_b64 exec, exec, s[4:5]
	s_waitcnt vmcnt(0)
	v_add_u32_e32 v146, 1, v158
	v_cmp_lt_i32_e32 vcc, 1, v146
	v_add_u32_e32 v146, -1, v158
	v_cmp_gt_u32_e64 s[0:1], s34, v146
	s_and_b64 vcc, vcc, s[0:1]
	v_add_u32_e32 v144, 2, v158
	s_nop 3
	v_cmp_lt_i32_e32 vcc, 1, v144
	v_cmp_ge_i32_e64 s[0:1], s34, v144
	s_and_b64 vcc, vcc, s[0:1]
	v_or_b32_e32 v190, 3, v160
	s_nop 0
	v_add_u32_e32 v136, s72, v190
	s_nop 2
	v_cmp_lt_i32_e32 vcc, 1, v136
	v_add_u32_e32 v136, -2, v136
	v_cmp_gt_u32_e64 s[0:1], s34, v136
	s_and_b64 vcc, vcc, s[0:1]
	v_add_u32_e32 v66, 4, v158
	s_nop 4
	v_cmp_lt_i32_e32 vcc, 1, v66
	v_cmp_ge_i32_e64 s[0:1], s34, v66
	s_and_b64 vcc, vcc, s[0:1]
	v_add_u32_e32 v74, 5, v158
	s_nop 4
	v_cmp_lt_i32_e32 vcc, 1, v74
	v_add_u32_e32 v74, 3, v158
	v_cmp_gt_u32_e64 s[0:1], s34, v74
	s_and_b64 vcc, vcc, s[0:1]
	v_add_u32_e32 v126, 6, v158
	s_nop 4
	v_cmp_lt_i32_e32 vcc, 1, v126
	v_cmp_ge_i32_e64 s[0:1], s34, v126
	s_and_b64 vcc, vcc, s[0:1]
	v_or_b32_e32 v159, 7, v159
	s_nop 0
	v_add_u32_e32 v122, s72, v159
	s_nop 2
	v_cmp_lt_i32_e32 vcc, 1, v122
	v_add_u32_e32 v122, -2, v122
	v_cmp_gt_u32_e64 s[0:1], s34, v122
	s_and_b64 vcc, vcc, s[0:1]
	s_nop 4
	s_movk_i32 s0, 0xf9d0
	v_add_u32_e32 v66, 8, v158
	v_cmp_lt_i32_e32 vcc, 1, v66
	s_nop 3
	v_cmp_ge_i32_e64 s[0:1], s34, v66
	s_and_b64 vcc, vcc, s[0:1]
	v_add_u32_e32 v74, 9, v158
	s_nop 4
	v_cmp_lt_i32_e32 vcc, 1, v74
	v_add_u32_e32 v74, 7, v158
	s_nop 1
	v_cmp_gt_u32_e64 s[0:1], s34, v74
	s_nop 1
	s_and_b64 vcc, vcc, s[0:1]
	v_add_u32_e32 v110, 10, v158
	s_nop 4
	v_cmp_lt_i32_e32 vcc, 1, v110
	v_cmp_ge_i32_e64 s[0:1], s34, v110
	s_and_b64 vcc, vcc, s[0:1]
	v_mul_f32_e32 v72, 0xbfb8aa3b, v157
	s_nop 2
	v_exp_f32_e32 v72, v72
	s_nop 5
	v_add_f32_e32 v68, 1.0, v72
	v_add_f32_e32 v66, -1.0, v68
	v_sub_f32_e32 v67, v66, v68
	v_add_f32_e32 v67, 1.0, v67
	v_sub_f32_e32 v66, v72, v66
	v_add_f32_e32 v69, v66, v67
	v_frexp_mant_f32_e32 v70, v68
	v_cvt_f64_f32_e32 v[66:67], v68
	s_mov_b32 s0, 0x3f2aaaab
	v_frexp_exp_i32_f64_e32 v66, v[66:67]
	v_cmp_gt_f32_e32 vcc, s0, v70
	s_mov_b32 s5, 0x3f317218
	v_mov_b32_e32 v85, 0x3ecc95a3
	v_subbrev_co_u32_e32 v66, vcc, 0, v66, vcc
	v_sub_u32_e32 v67, 0, v66
	v_ldexp_f32 v68, v68, v67
	v_ldexp_f32 v67, v69, v67
	v_add_f32_e32 v69, -1.0, v68
	v_add_f32_e32 v73, 1.0, v68
	v_add_f32_e32 v70, 1.0, v69
	v_add_f32_e32 v74, -1.0, v73
	v_sub_f32_e32 v70, v68, v70
	v_sub_f32_e32 v68, v68, v74
	v_add_f32_e32 v70, v67, v70
	v_add_f32_e32 v67, v67, v68
	v_add_f32_e32 v68, v73, v67
	v_rcp_f32_e32 v74, v68
	v_add_f32_e32 v71, v69, v70
	v_sub_f32_e32 v69, v71, v69
	v_sub_f32_e32 v69, v70, v69
	v_sub_f32_e32 v70, v68, v73
	v_sub_f32_e32 v67, v67, v70
	v_mul_f32_e32 v70, v71, v74
	v_mul_f32_e32 v73, v68, v70
	v_fma_f32 v75, v70, v68, -v73
	v_fmac_f32_e32 v75, v70, v67
	v_add_f32_e32 v76, v73, v75
	v_sub_f32_e32 v77, v71, v76
	v_sub_f32_e32 v71, v71, v77
	v_sub_f32_e32 v73, v76, v73
	v_sub_f32_e32 v71, v71, v76
	v_add_f32_e32 v69, v69, v71
	v_sub_f32_e32 v71, v73, v75
	v_add_f32_e32 v69, v71, v69
	v_add_f32_e32 v71, v77, v69
	v_mul_f32_e32 v73, v74, v71
	v_mul_f32_e32 v75, v68, v73
	v_fma_f32 v68, v73, v68, -v75
	v_fmac_f32_e32 v68, v73, v67
	v_sub_f32_e32 v67, v77, v71
	v_add_f32_e32 v67, v69, v67
	v_add_f32_e32 v69, v75, v68
	v_sub_f32_e32 v76, v71, v69
	v_sub_f32_e32 v71, v71, v76
	v_sub_f32_e32 v75, v69, v75
	v_sub_f32_e32 v69, v71, v69
	v_add_f32_e32 v67, v67, v69
	v_sub_f32_e32 v68, v75, v68
	v_cvt_f32_i32_e32 v66, v66
	v_add_f32_e32 v67, v68, v67
	v_add_f32_e32 v68, v70, v73
	v_add_f32_e32 v67, v76, v67
	v_sub_f32_e32 v69, v68, v70
	v_mul_f32_e32 v67, v74, v67
	v_sub_f32_e32 v69, v73, v69
	v_add_f32_e32 v67, v69, v67
	v_mul_f32_e32 v73, 0x3f317218, v66
	v_add_f32_e32 v69, v68, v67
	v_fma_f32 v74, v66, s5, -v73
	v_mul_f32_e32 v70, v69, v69
	v_fmac_f32_e32 v74, 0xb102e308, v66
	v_sub_f32_e32 v66, v69, v68
	v_fmamk_f32 v71, v70, 0x3e9b6dac, v85
	v_sub_f32_e32 v66, v67, v66
	v_add_f32_e32 v67, v73, v74
	v_fmaak_f32 v71, v70, v71, 0x3f2aaada
	v_sub_f32_e32 v68, v67, v73
	v_ldexp_f32 v73, v69, 1
	v_mul_f32_e32 v69, v69, v70
	v_mul_f32_e32 v69, v69, v71
	v_add_f32_e32 v70, v73, v69
	v_sub_f32_e32 v71, v70, v73
	v_ldexp_f32 v66, v66, 1
	v_sub_f32_e32 v69, v69, v71
	v_add_f32_e32 v66, v66, v69
	v_add_f32_e32 v69, v70, v66
	v_sub_f32_e32 v70, v69, v70
	v_sub_f32_e32 v66, v66, v70
	v_add_f32_e32 v70, v67, v69
	v_sub_f32_e32 v71, v70, v67
	v_sub_f32_e32 v73, v70, v71
	v_sub_f32_e32 v68, v74, v68
	v_sub_f32_e32 v67, v67, v73
	v_sub_f32_e32 v69, v69, v71
	v_add_f32_e32 v67, v69, v67
	v_add_f32_e32 v69, v68, v66
	v_sub_f32_e32 v71, v69, v68
	v_sub_f32_e32 v73, v69, v71
	v_sub_f32_e32 v68, v68, v73
	v_sub_f32_e32 v66, v66, v71
	v_add_f32_e32 v67, v69, v67
	v_add_f32_e32 v66, v66, v68
	v_add_f32_e32 v68, v70, v67
	v_sub_f32_e32 v69, v68, v70
	v_sub_f32_e32 v67, v67, v69
	v_add_f32_e32 v66, v66, v67
	s_mov_b32 s1, 0x7f800000
	v_add_f32_e32 v66, v68, v66
	v_cmp_neq_f32_e32 vcc, s1, v72
	v_mov_b32_e32 v67, 0x7f800000
	s_mov_b32 s1, 0x33800000
	v_cndmask_b32_e32 v66, v67, v66, vcc
	v_cmp_ngt_f32_e32 vcc, -1.0, v72
	v_mov_b32_e32 v67, 0x7fc00000
	s_waitcnt lgkmcnt(0)
	v_cndmask_b32_e32 v66, v67, v66, vcc
	v_cmp_neq_f32_e32 vcc, -1.0, v72
	v_mov_b32_e32 v67, 0xff800000
	s_barrier
; template <int MODE>
; __device__ __forceinline__ void lru_unit(const Args& a, LAS unsigned char* lds, int l, int tt) {
;     ...
;     for (int nt = 0; nt < 2; ++nt) { prm0[nt][2] = -8.0f * log1pf(__expf(-prm0[nt][2])); prm1[nt][2] = -8.0f * log1pf(__expf(-prm1[nt][2])); }
	v_cndmask_b32_e32 v66, v67, v66, vcc
	v_mul_f32_e32 v67, 0xbfb8aa3b, v156
	v_exp_f32_e32 v183, v67
	v_cmp_lt_f32_e64 vcc, |v72|, s1
	s_movk_i32 s28, 0x210
	s_nop 0
	v_cndmask_b32_e32 v66, v66, v72, vcc
	v_add_f32_e32 v68, 1.0, v183
	v_mul_f32_e32 v214, 0xc1000000, v66
	v_add_f32_e32 v66, -1.0, v68
	v_sub_f32_e32 v67, v66, v68
	v_add_f32_e32 v67, 1.0, v67
	v_sub_f32_e32 v66, v183, v66
	v_add_f32_e32 v69, v66, v67
	v_frexp_mant_f32_e32 v70, v68
	v_cvt_f64_f32_e32 v[66:67], v68
	v_frexp_exp_i32_f64_e32 v66, v[66:67]
	v_cmp_gt_f32_e32 vcc, s0, v70
	s_nop 1
	v_subbrev_co_u32_e32 v66, vcc, 0, v66, vcc
	v_sub_u32_e32 v67, 0, v66
	v_ldexp_f32 v68, v68, v67
	v_ldexp_f32 v67, v69, v67
	v_add_f32_e32 v69, -1.0, v68
	v_add_f32_e32 v72, 1.0, v68
	v_add_f32_e32 v70, 1.0, v69
	v_add_f32_e32 v73, -1.0, v72
	v_sub_f32_e32 v70, v68, v70
	v_sub_f32_e32 v68, v68, v73
	v_add_f32_e32 v70, v67, v70
	v_add_f32_e32 v67, v67, v68
	v_add_f32_e32 v68, v72, v67
	v_rcp_f32_e32 v73, v68
	v_add_f32_e32 v71, v69, v70
	v_sub_f32_e32 v69, v71, v69
	v_sub_f32_e32 v69, v70, v69
	v_sub_f32_e32 v70, v68, v72
	v_sub_f32_e32 v67, v67, v70
	v_mul_f32_e32 v70, v71, v73
	v_mul_f32_e32 v72, v68, v70
	v_fma_f32 v74, v70, v68, -v72
	v_fmac_f32_e32 v74, v70, v67
	v_add_f32_e32 v75, v72, v74
	v_sub_f32_e32 v76, v71, v75
	v_sub_f32_e32 v71, v71, v76
	v_sub_f32_e32 v72, v75, v72
	v_sub_f32_e32 v71, v71, v75
	v_add_f32_e32 v69, v69, v71
	v_sub_f32_e32 v71, v72, v74
	v_add_f32_e32 v69, v71, v69
	v_add_f32_e32 v71, v76, v69
	v_mul_f32_e32 v72, v73, v71
	v_mul_f32_e32 v74, v68, v72
	v_fma_f32 v68, v72, v68, -v74
	v_fmac_f32_e32 v68, v72, v67
	v_sub_f32_e32 v67, v76, v71
	v_add_f32_e32 v67, v69, v67
	v_add_f32_e32 v69, v74, v68
	v_sub_f32_e32 v75, v71, v69
	v_sub_f32_e32 v71, v71, v75
	v_sub_f32_e32 v74, v69, v74
	v_sub_f32_e32 v69, v71, v69
	v_add_f32_e32 v67, v67, v69
	v_sub_f32_e32 v68, v74, v68
	v_cvt_f32_i32_e32 v66, v66
	v_add_f32_e32 v67, v68, v67
	v_add_f32_e32 v68, v70, v72
	v_add_f32_e32 v67, v75, v67
	v_sub_f32_e32 v69, v68, v70
	v_mul_f32_e32 v67, v73, v67
	v_sub_f32_e32 v69, v72, v69
	v_add_f32_e32 v67, v69, v67
	v_mul_f32_e32 v194, 0x3f317218, v66
	v_add_f32_e32 v191, v68, v67
	v_fma_f32 v195, v66, s5, -v194
	v_fmac_f32_e32 v195, 0xb102e308, v66
	v_sub_f32_e32 v66, v191, v68
	v_sub_f32_e32 v66, v67, v66
	v_mul_f32_e32 v67, 0xbfb8aa3b, v155
	v_exp_f32_e32 v76, v67
	v_ldexp_f32 v196, v66, 1
	v_mul_f32_e32 v192, v191, v191
	v_fmamk_f32 v69, v192, 0x3e9b6dac, v85
	v_add_f32_e32 v68, 1.0, v76
	v_add_f32_e32 v66, -1.0, v68
	v_sub_f32_e32 v67, v66, v68
	v_add_f32_e32 v67, 1.0, v67
	v_sub_f32_e32 v66, v76, v66
	v_fmaak_f32 v193, v192, v69, 0x3f2aaada
	v_add_f32_e32 v69, v66, v67
	v_frexp_mant_f32_e32 v70, v68
	v_cvt_f64_f32_e32 v[66:67], v68
	v_frexp_exp_i32_f64_e32 v66, v[66:67]
	v_cmp_gt_f32_e32 vcc, s0, v70
	v_ldexp_f32 v197, v191, 1
	s_nop 0
	v_subbrev_co_u32_e32 v66, vcc, 0, v66, vcc
	v_sub_u32_e32 v67, 0, v66
	v_ldexp_f32 v68, v68, v67
	v_ldexp_f32 v67, v69, v67
	v_add_f32_e32 v69, -1.0, v68
	v_add_f32_e32 v72, 1.0, v68
	v_add_f32_e32 v70, 1.0, v69
	v_add_f32_e32 v73, -1.0, v72
	v_sub_f32_e32 v70, v68, v70
	v_sub_f32_e32 v68, v68, v73
	v_add_f32_e32 v70, v67, v70
	v_add_f32_e32 v67, v67, v68
	v_add_f32_e32 v68, v72, v67
	v_rcp_f32_e32 v73, v68
	v_add_f32_e32 v71, v69, v70
	v_sub_f32_e32 v69, v71, v69
	v_sub_f32_e32 v69, v70, v69
	v_sub_f32_e32 v70, v68, v72
	v_sub_f32_e32 v67, v67, v70
	v_mul_f32_e32 v70, v71, v73
	v_mul_f32_e32 v72, v68, v70
	v_fma_f32 v74, v70, v68, -v72
	v_fmac_f32_e32 v74, v70, v67
	v_add_f32_e32 v75, v72, v74
	v_sub_f32_e32 v77, v71, v75
	v_sub_f32_e32 v71, v71, v77
	v_sub_f32_e32 v72, v75, v72
	v_sub_f32_e32 v71, v71, v75
	v_add_f32_e32 v69, v69, v71
	v_sub_f32_e32 v71, v72, v74
	v_add_f32_e32 v69, v71, v69
	v_add_f32_e32 v71, v77, v69
	v_mul_f32_e32 v72, v73, v71
	v_mul_f32_e32 v74, v68, v72
	v_fma_f32 v68, v72, v68, -v74
	v_fmac_f32_e32 v68, v72, v67
	v_sub_f32_e32 v67, v77, v71
	v_add_f32_e32 v67, v69, v67
	v_add_f32_e32 v69, v74, v68
	v_sub_f32_e32 v75, v71, v69
	v_sub_f32_e32 v71, v71, v75
	v_sub_f32_e32 v74, v69, v74
	v_sub_f32_e32 v69, v71, v69
	v_add_f32_e32 v67, v67, v69
	v_sub_f32_e32 v68, v74, v68
	v_cvt_f32_i32_e32 v66, v66
	v_add_f32_e32 v67, v68, v67
	v_add_f32_e32 v68, v70, v72
	v_add_f32_e32 v67, v75, v67
	v_sub_f32_e32 v69, v68, v70
	v_mul_f32_e32 v67, v73, v67
	v_sub_f32_e32 v69, v72, v69
	v_add_f32_e32 v67, v69, v67
	v_mul_f32_e32 v81, 0x3f317218, v66
	v_add_f32_e32 v78, v68, v67
	v_fma_f32 v82, v66, s5, -v81
	v_fmac_f32_e32 v82, 0xb102e308, v66
	v_sub_f32_e32 v66, v78, v68
	v_sub_f32_e32 v66, v67, v66
	v_mul_f32_e32 v67, 0xbfb8aa3b, v154
	v_exp_f32_e32 v181, v67
	v_ldexp_f32 v83, v66, 1
	v_mul_f32_e32 v79, v78, v78
	v_fmamk_f32 v69, v79, 0x3e9b6dac, v85
	v_add_f32_e32 v68, 1.0, v181
	v_add_f32_e32 v66, -1.0, v68
	v_sub_f32_e32 v67, v66, v68
	v_add_f32_e32 v67, 1.0, v67
	v_sub_f32_e32 v66, v181, v66
	v_fmaak_f32 v80, v79, v69, 0x3f2aaada
	v_add_f32_e32 v69, v66, v67
	v_frexp_mant_f32_e32 v70, v68
	v_cvt_f64_f32_e32 v[66:67], v68
	v_frexp_exp_i32_f64_e32 v66, v[66:67]
	v_cmp_gt_f32_e32 vcc, s0, v70
	v_ldexp_f32 v92, v78, 1
	v_and_b32_e32 v77, 0x7fffffff, v76
	v_subbrev_co_u32_e32 v66, vcc, 0, v66, vcc
	v_sub_u32_e32 v67, 0, v66
	v_ldexp_f32 v68, v68, v67
	v_ldexp_f32 v67, v69, v67
	v_add_f32_e32 v69, -1.0, v68
	v_add_f32_e32 v72, 1.0, v68
	v_add_f32_e32 v70, 1.0, v69
	v_add_f32_e32 v73, -1.0, v72
	v_sub_f32_e32 v70, v68, v70
	v_sub_f32_e32 v68, v68, v73
	v_add_f32_e32 v70, v67, v70
	v_add_f32_e32 v67, v67, v68
	v_add_f32_e32 v68, v72, v67
	v_rcp_f32_e32 v73, v68
	v_add_f32_e32 v71, v69, v70
	v_sub_f32_e32 v69, v71, v69
	v_sub_f32_e32 v69, v70, v69
; #define LAS __attribute__((address_space(3)))
; __device__ __forceinline__ float fsig(float x) { return frcp(1.0f + __expf(-x)); }
; template <int DIR, int MODE>
; __device__ __forceinline__ void lru_pass(const Args& a, const LAS bf16_t* cxb, LAS bf16_t* gyb, const LAS float* carry, const bf16x8 (&Bw)[2][2][2], const float (&prm)[2][3], int l, int tt, float (&hf)[8][2][4]) {
;     ...
;     for (int mi = 0; mi < 8; ++mi) {
;         const int m = DIR ? 7 - mi : mi;
;         bf16x8 Af[2];
; #pragma unroll
;         for (int ks = 0; ks < 2; ++ks) Af[ks] = *(const LAS bf16x8*)(cxb + (m * 16 + fr) * CXS + 64 * h + 32 * ks + 8 * fq);
; #pragma unroll
;         for (int nt = 0; nt < 2; ++nt) {
;             f32x4 pr = (f32x4){0.f, 0.f, 0.f, 0.f}, pi = (f32x4){0.f, 0.f, 0.f, 0.f};
; #pragma unroll
;             for (int ks = 0; ks < 2; ++ks) { pr = __builtin_amdgcn_mfma_f32_16x16x32_bf16(Af[ks], Bw[0][nt][ks], pr, 0, 0, 0); pi = __builtin_amdgcn_mfma_f32_16x16x32_bf16(Af[ks], Bw[1][nt][ks], pi, 0, 0, 0); }
;             float av[4], bv[4];
; #pragma unroll
;             for (int reg = 0; reg < 4; ++reg) {
;                 const int tok = m * 16 + 4 * fq + reg;
;                 const float x = bf2f(cxb[tok * CXS + cc[nt]]);
;                 const float r = fsig(pr[reg] + ba[nt]), ig = fsig(pi[reg] + bxv[nt]);
;                 const float aa = __expf(k8[nt] * r);
;                 av[reg] = aa; bv[reg] = __builtin_amdgcn_sqrtf(fmaxf(1.0f - aa * aa, 0.f)) * ig * x;
;             }
;             float cum[4], hl[4];
;             if (DIR == 0) { cum[0] = av[0]; hl[0] = bv[0];
; #pragma unroll
;                 for (int reg = 1; reg < 4; ++reg) { cum[reg] = cum[reg - 1] * av[reg]; hl[reg] = av[reg] * hl[reg - 1] + bv[reg]; } }
;             else { cum[3] = av[3]; hl[3] = bv[3];
; #pragma unroll
;     ...
;             const float A4 = DIR ? cum[0] : cum[3], H4 = DIR ? hl[0] : hl[3];
;             float Aq[4], Hq[4];
; #pragma unroll
;             for (int q = 0; q < 4; ++q) { Aq[q] = __shfl(A4, fr + 16 * q); Hq[q] = __shfl(H4, fr + 16 * q); }
;             float hin;
;             if (DIR == 0) { const float s0 = C[nt], s1 = Aq[0] * s0 + Hq[0], s2 = Aq[1] * s1 + Hq[1], s3 = Aq[2] * s2 + Hq[2]; C[nt] = Aq[3] * s3 + Hq[3]; hin = fq == 0 ? s0 : (fq == 1 ? s1 : (fq == 2 ? s2 : s3)); }
	v_sub_f32_e32 v70, v68, v72
	v_sub_f32_e32 v67, v67, v70
	v_mul_f32_e32 v70, v71, v73
	v_mul_f32_e32 v72, v68, v70
	v_fma_f32 v74, v70, v68, -v72
	v_fmac_f32_e32 v74, v70, v67
	v_add_f32_e32 v75, v72, v74
	v_sub_f32_e32 v84, v71, v75
	v_sub_f32_e32 v71, v71, v84
	v_sub_f32_e32 v72, v75, v72
	v_sub_f32_e32 v71, v71, v75
	v_add_f32_e32 v69, v69, v71
	v_sub_f32_e32 v71, v72, v74
	v_add_f32_e32 v69, v71, v69
	v_add_f32_e32 v71, v84, v69
	v_mul_f32_e32 v72, v73, v71
	v_mul_f32_e32 v74, v68, v72
	v_fma_f32 v68, v72, v68, -v74
	v_fmac_f32_e32 v68, v72, v67
	v_sub_f32_e32 v67, v84, v71
	v_add_f32_e32 v67, v69, v67
	v_add_f32_e32 v69, v74, v68
	v_sub_f32_e32 v75, v71, v69
	v_sub_f32_e32 v71, v71, v75
	v_sub_f32_e32 v74, v69, v74
	v_sub_f32_e32 v69, v71, v69
	v_add_f32_e32 v67, v67, v69
	v_sub_f32_e32 v68, v74, v68
	v_add_f32_e32 v67, v68, v67
	v_add_f32_e32 v68, v70, v72
	v_add_f32_e32 v67, v75, v67
	v_sub_f32_e32 v69, v68, v70
	v_mul_f32_e32 v67, v73, v67
	v_sub_f32_e32 v69, v72, v69
	v_add_f32_e32 v67, v69, v67
	v_mov_b32_e32 v69, v0
	v_cvt_f32_i32_e32 v66, v66
	v_readfirstlane_b32 s0, v69
	s_bfe_u32 s1, s0, 0x20006
	s_lshl_b32 s4, s1, 7
	v_bfe_u32 v200, v69, 4, 2
	s_add_i32 s4, s4, 0
	v_and_b32_e32 v75, 15, v69
	v_lshl_add_u32 v93, v200, 4, s4
	v_mad_u32_u24 v69, v75, s29, v93
	ds_read_b128 v[70:73], v69
	v_add_f32_e32 v184, v68, v67
	v_mul_f32_e32 v187, 0x3f317218, v66
	v_mul_f32_e32 v185, v184, v184
	v_fma_f32 v188, v66, s5, -v187
	v_fmamk_f32 v74, v185, 0x3e9b6dac, v85
	v_fmac_f32_e32 v188, 0xb102e308, v66
	v_sub_f32_e32 v66, v184, v68
	v_fmaak_f32 v186, v185, v74, 0x3f2aaada
	v_sub_f32_e32 v74, v67, v66
	ds_read_b128 v[66:69], v69 offset:64
	s_waitcnt lgkmcnt(1)
	v_mfma_f32_16x16x32_bf16 v[84:87], v[70:73], v[50:53], 0
	s_ashr_i32 s0, s0, 3
	s_lshl_b32 s1, s1, 6
	s_andn2_b32 s0, s0, 31
	s_waitcnt lgkmcnt(0)
	v_mfma_f32_16x16x32_bf16 v[94:97], v[66:69], v[54:57], v[84:87]
	s_nop 2
	v_and_b32_e32 v84, 64, v227
	v_or_b32_e32 v98, v84, v75
	s_add_i32 s1, s1, s0
	s_nop 1
	v_add_f32_e32 v84, v171, v94
	v_mul_f32_e32 v84, 0xbfb8aa3b, v84
	v_exp_f32_e32 v84, v84
	v_mfma_f32_16x16x32_bf16 v[88:91], v[70:73], v[58:61], 0
	v_ldexp_f32 v189, v74, 1
	v_or_b32_e32 v74, s1, v75
	v_add_f32_e32 v84, 1.0, v84
	v_rcp_f32_e32 v84, v84
	v_mfma_f32_16x16x32_bf16 v[88:91], v[66:69], v[62:65], v[88:91]
	v_lshlrev_b32_e32 v85, 1, v74
	v_mul_u32_u24_e32 v86, 0x840, v200
	v_mul_f32_e32 v84, v214, v84
	v_add3_u32 v213, 0, v85, v86
	v_mul_f32_e32 v84, 0x3fb8aa3b, v84
	s_nop 2
	v_add_f32_e32 v85, v170, v88
	v_mul_f32_e32 v85, 0xbfb8aa3b, v85
	v_exp_f32_e32 v87, v84
	v_exp_f32_e32 v85, v85
	ds_read_u16 v84, v213
	v_add_f32_e32 v88, v170, v89
	v_fma_f32 v86, -v87, v87, 1.0
	v_add_f32_e32 v85, 1.0, v85
	v_max_f32_e32 v86, 0, v86
	v_rcp_f32_e32 v85, v85
	v_sqrt_f32_e32 v86, v86
	s_waitcnt lgkmcnt(0)
	v_lshlrev_b32_e32 v84, 16, v84
	v_mul_f32_e32 v88, 0xbfb8aa3b, v88
	v_exp_f32_e32 v89, v88
	v_mul_f32_e32 v85, v85, v86
	v_add_f32_e32 v86, v171, v95
	v_mul_f32_e32 v86, 0xbfb8aa3b, v86
	v_exp_f32_e32 v86, v86
	v_mul_f32_e32 v88, v85, v84
	v_add_f32_e32 v84, 1.0, v89
	v_add_f32_e32 v90, v170, v90
	v_add_f32_e32 v86, 1.0, v86
	v_rcp_f32_e32 v86, v86
	v_mul_f32_e32 v90, 0xbfb8aa3b, v90
	v_rcp_f32_e32 v84, v84
	v_exp_f32_e32 v90, v90
	v_mul_f32_e32 v85, v214, v86
	v_add_f32_e32 v86, v171, v96
	v_mul_f32_e32 v86, 0xbfb8aa3b, v86
	v_exp_f32_e32 v86, v86
	v_mul_f32_e32 v85, 0x3fb8aa3b, v85
	v_exp_f32_e32 v85, v85
	v_add_f32_e32 v91, v170, v91
	v_add_f32_e32 v86, 1.0, v86
	v_rcp_f32_e32 v86, v86
	v_fma_f32 v89, -v85, v85, 1.0
	v_max_f32_e32 v89, 0, v89
	v_sqrt_f32_e32 v89, v89
	v_mul_f32_e32 v86, v214, v86
	v_mul_f32_e32 v86, 0x3fb8aa3b, v86
	v_exp_f32_e32 v95, v86
	v_add_f32_e32 v86, v171, v97
	v_mul_f32_e32 v86, 0xbfb8aa3b, v86
	v_exp_f32_e32 v86, v86
	v_mul_f32_e32 v91, 0xbfb8aa3b, v91
	v_mul_f32_e32 v84, v84, v89
	v_add_f32_e32 v89, 1.0, v90
	v_add_f32_e32 v86, 1.0, v86
	v_rcp_f32_e32 v86, v86
	v_fma_f32 v90, -v95, v95, 1.0
	v_exp_f32_e32 v91, v91
	v_max_f32_e32 v90, 0, v90
	v_mul_f32_e32 v86, v214, v86
	v_mul_f32_e32 v86, 0x3fb8aa3b, v86
	v_exp_f32_e32 v96, v86
	ds_read_u16 v94, v213 offset:528
	ds_read_u16 v99, v213 offset:1056
	ds_read_u16 v100, v213 offset:1584
	v_rcp_f32_e32 v89, v89
	v_sqrt_f32_e32 v86, v90
	v_add_f32_e32 v90, 1.0, v91
	v_fma_f32 v91, -v96, v96, 1.0
	v_max_f32_e32 v91, 0, v91
	s_waitcnt lgkmcnt(2)
	v_lshlrev_b32_e32 v94, 16, v94
	v_rcp_f32_e32 v90, v90
	v_sqrt_f32_e32 v91, v91
	s_waitcnt lgkmcnt(1)
	v_lshlrev_b32_e32 v97, 16, v99
	v_mul_f32_e32 v99, v89, v86
	v_mul_f32_e32 v86, v85, v88
	v_fmac_f32_e32 v86, v84, v94
	v_mul_f32_e32 v89, v85, v87
	v_mul_f32_e32 v85, v95, v86
	v_fmac_f32_e32 v85, v99, v97
	s_waitcnt lgkmcnt(0)
	v_lshlrev_b32_e32 v100, 16, v100
	v_mul_f32_e32 v101, v90, v91
	v_mul_f32_e32 v90, v95, v89
	v_mul_f32_e32 v84, v96, v85
	v_lshl_add_u32 v74, v74, 2, 0
	v_mul_f32_e32 v91, v96, v90
	v_fmac_f32_e32 v84, v101, v100
	v_lshlrev_b32_e32 v210, 2, v98
	v_add_u32_e32 v74, 0x21000, v74
	ds_bpermute_b32 v99, v210, v91
	ds_bpermute_b32 v97, v210, v84
	v_mul_u32_u24_e32 v96, 0x210, v75
	ds_read2_b32 v[74:75], v74 offset1:16
	ds_bpermute_b32 v100, v210, v91 offset:64
	ds_bpermute_b32 v98, v210, v84 offset:64
	ds_bpermute_b32 v102, v210, v91 offset:128
	ds_bpermute_b32 v94, v210, v84 offset:128
	ds_bpermute_b32 v95, v210, v91 offset:192
	ds_bpermute_b32 v101, v210, v84 offset:192
	s_waitcnt lgkmcnt(6)
	v_fmac_f32_e32 v97, v74, v99
	s_waitcnt lgkmcnt(4)
	v_fmac_f32_e32 v98, v97, v100
	v_ldexp_f32 v190, v184, 1
	v_or_b32_e32 v212, 64, v210
	v_or_b32_e32 v211, 0x80, v210
	v_or_b32_e32 v218, 0xc0, v210
	v_cmp_eq_u32_e32 vcc, 2, v200
	s_waitcnt lgkmcnt(2)
	v_fmac_f32_e32 v94, v98, v102
	v_cmp_lt_i32_e64 s[0:1], 0, v200
	s_and_saveexec_b64 s[4:5], s[0:1]
	s_cbranch_execz .LBB0_551
	v_cmp_ne_u32_e64 s[0:1], 1, v200
	s_and_saveexec_b64 s[34:35], s[0:1]
	s_xor_b64 s[0:1], exec, s[34:35]
	v_cndmask_b32_e32 v74, v94, v98, vcc
	s_andn2_saveexec_b64 s[0:1], s[0:1]
	v_mov_b32_e32 v74, v97
	s_or_b64 exec, exec, s[0:1]
